# GEMM phase prologues: second staging batch issued before the first wait+barrier
# speedup vs baseline: 1.0191x; 1.0001x over previous
.LBB0_206:
	s_lshl_b32 s10, s10, 5
	s_and_b32 s16, s10, 0x60
	s_mov_b64 s[10:11], 0x80
	s_add_i32 m0, s23, 0x18000
	v_lshl_add_u64 v[8:9], v[8:9], 0, s[10:11]
	s_lshl_b32 s13, s12, 13
	s_lshl_b32 s17, s16, 7
	global_load_lds_dwordx4 v[8:9], off
	v_lshl_add_u64 v[6:7], v[6:7], 0, s[10:11]
	s_add_i32 m0, s23, 0x1a000
	s_add_i32 s37, s23, 0x8000
	s_add_i32 s38, s23, 0xa000
	global_load_lds_dwordx4 v[6:7], off
	v_lshl_add_u64 v[2:3], v[2:3], 0, s[10:11]
	s_mov_b32 m0, s37
	s_add_u32 s14, s26, 0x40080
	global_load_lds_dwordx4 v[2:3], off
	v_lshl_add_u64 v[2:3], v[4:5], 0, s[10:11]
	s_mov_b32 m0, s38
	s_addc_u32 s15, s27, 0
	global_load_lds_dwordx4 v[2:3], off
	s_add_i32 m0, s23, 0x1c000
	v_lshl_add_u64 v[2:3], s[14:15], 0, v[134:135]
	global_load_lds_dwordx4 v[2:3], off
	v_lshl_add_u64 v[2:3], s[14:15], 0, v[130:131]
	s_add_i32 m0, s23, 0x1e000
	s_sext_i32_i8 s43, s0
	global_load_lds_dwordx4 v[2:3], off
	s_waitcnt vmcnt(8)
	s_barrier
	v_and_b32_e32 v1, 15, v170
	v_lshlrev_b32_e32 v2, 1, v13
	v_lshlrev_b32_e32 v4, 6, v170
	s_movk_i32 s0, 0x3c0
	v_lshl_or_b32 v150, s12, 6, v1
	v_lshl_or_b32 v1, v1, 6, v2
	v_and_b32_e32 v3, 32, v172
	v_and_or_b32 v2, v4, s0, v2
	v_bitop3_b32 v151, s17, v2, v3 bitop3:0xf6
	v_lshlrev_b32_e32 v2, 8, v170
	v_bitop3_b32 v1, v1, s13, v3 bitop3:0xde
	v_and_b32_e32 v2, 0x38000, v2
	v_lshlrev_b32_e32 v3, 11, v14
	v_or3_b32 v2, v11, v2, v3
	v_add_u32_e32 v138, v2, v12
	v_lshlrev_b32_e32 v2, 4, v10
	s_waitcnt vmcnt(6)
	s_cmpk_lt_u32 s1, 0x100
	v_and_b32_e32 v2, 0x78000, v2
	s_cselect_b64 s[12:13], -1, 0
	v_or3_b32 v2, v11, v2, v3
	s_add_i32 s40, 0, 0x10000
	s_add_i32 s41, 0, 0x14000
	s_ashr_i32 s39, s33, 31
	v_or_b32_e32 v152, s16, v13
	v_mov_b32_e32 v139, v135
	v_add_u32_e32 v140, v2, v12
	v_mov_b32_e32 v141, v135
	v_mov_b64_e32 v[142:143], 0x180
	v_mov_b64_e32 v[144:145], 0x17f
	v_add_u32_e32 v153, s40, v151
	v_add_u32_e32 v154, s41, v151
	v_add_u32_e32 v155, 0, v1
	s_movk_i32 s42, 0xc00
	s_barrier
	s_branch .LBB0_209

.LBB0_440:
	s_add_u32 s43, s88, 0x1c2000
	s_addc_u32 s44, s89, 0
	s_lshl_b32 s1, s1, 5
	s_and_b32 s18, s1, 0x60
	s_lshl_b32 s17, s0, 13
	s_lshl_b32 s1, s18, 7
	s_add_u32 s45, s88, 0x2c0000
	s_mov_b64 s[14:15], 0x80
	s_addc_u32 s46, s89, 0
	s_add_i32 m0, s38, 0x18000
	v_lshl_add_u64 v[8:9], v[8:9], 0, s[14:15]
	global_load_lds_dwordx4 v[8:9], off
	v_lshl_add_u64 v[6:7], v[6:7], 0, s[14:15]
	s_add_i32 m0, s38, 0x1a000
	s_add_i32 s47, s38, 0x8000
	s_add_i32 s48, s38, 0xa000
	global_load_lds_dwordx4 v[6:7], off
	v_lshl_add_u64 v[2:3], v[2:3], 0, s[14:15]
	s_mov_b32 m0, s47
	s_add_u32 s4, s34, 0x40080
	global_load_lds_dwordx4 v[2:3], off
	v_lshl_add_u64 v[2:3], v[4:5], 0, s[14:15]
	s_mov_b32 m0, s48
	s_addc_u32 s5, s35, 0
	global_load_lds_dwordx4 v[2:3], off
	s_add_i32 m0, s38, 0x1c000
	v_lshl_add_u64 v[2:3], s[4:5], 0, v[164:165]
	global_load_lds_dwordx4 v[2:3], off
	v_lshl_add_u64 v[2:3], s[4:5], 0, v[168:169]
	s_add_i32 m0, s38, 0x1e000
	v_and_b32_e32 v1, 15, v170
	global_load_lds_dwordx4 v[2:3], off
	s_waitcnt vmcnt(8)
	s_barrier
	v_bfe_u32 v2, v170, 4, 2
	v_lshl_or_b32 v171, s0, 6, v1
	v_lshlrev_b32_e32 v3, 4, v2
	v_lshlrev_b32_e32 v5, 6, v170
	s_movk_i32 s0, 0x3c0
	v_lshl_or_b32 v1, v1, 6, v3
	v_and_b32_e32 v4, 32, v172
	v_and_or_b32 v3, v5, s0, v3
	v_bitop3_b32 v173, s1, v3, v4 bitop3:0xf6
	v_cmp_eq_u32_e64 s[0:1], 0, v2
	v_lshl_or_b32 v212, v2, 3, s18
	v_lshlrev_b32_e32 v2, 8, v170
	v_and_b32_e32 v2, 0x38000, v2
	v_lshlrev_b32_e32 v3, 11, v12
	v_or3_b32 v2, v10, v2, v3
	v_add_u32_e32 v174, v2, v11
	v_lshlrev_b32_e32 v2, 4, v13
	v_bitop3_b32 v1, v1, s17, v4 bitop3:0xde
	s_waitcnt vmcnt(6)
	s_cmpk_lt_u32 s16, 0x100
	v_and_b32_e32 v2, 0x78000, v2
	s_cselect_b64 s[16:17], -1, 0
	v_or3_b32 v2, v10, v2, v3
	s_add_i32 s51, 0, 0x10000
	s_add_i32 s54, 0, 0x14000
	v_add_u32_e32 v215, 0, v1
	v_mbcnt_lo_u32_b32 v1, -1, 0
	s_ashr_i32 s49, s33, 31
	s_ashr_i32 s50, s2, 31
	v_mov_b32_e32 v175, v165
	v_add_u32_e32 v176, v2, v11
	v_mov_b32_e32 v177, v165
	v_mov_b64_e32 v[178:179], 0x100
	v_mov_b64_e32 v[180:181], 0xff
	v_add_u32_e32 v213, s51, v173
	v_add_u32_e32 v214, s54, v173
	v_mbcnt_hi_u32_b32 v216, -1, v1
	s_barrier
	s_branch .LBB0_443

.LBB0_551:
	s_add_u32 s22, s88, 0x2a00000
	s_addc_u32 s23, s89, 0
	s_add_u32 s24, s88, 0x2d00000
	s_addc_u32 s25, s89, 0
	s_lshl_b32 s0, s7, 5
	s_mov_b64 s[26:27], 0x80
	s_and_b32 s7, s0, 0x60
	s_add_i32 m0, s70, 0x18000
	v_lshl_add_u64 v[8:9], v[8:9], 0, s[26:27]
	s_lshl_b32 s5, s6, 13
	s_lshl_b32 s12, s7, 7
	global_load_lds_dwordx4 v[8:9], off
	v_lshl_add_u64 v[6:7], v[6:7], 0, s[26:27]
	s_add_i32 m0, s70, 0x1a000
	s_add_i32 s77, s70, 0x8000
	s_add_i32 s78, s70, 0xa000
	global_load_lds_dwordx4 v[6:7], off
	v_lshl_add_u64 v[2:3], v[2:3], 0, s[26:27]
	s_mov_b32 m0, s77
	s_add_u32 s0, s48, 0x40080
	global_load_lds_dwordx4 v[2:3], off
	v_lshl_add_u64 v[2:3], v[4:5], 0, s[26:27]
	s_mov_b32 m0, s78
	s_addc_u32 s1, s49, 0
	global_load_lds_dwordx4 v[2:3], off
	s_add_i32 m0, s70, 0x1c000
	v_lshl_add_u64 v[2:3], s[0:1], 0, v[176:177]
	global_load_lds_dwordx4 v[2:3], off
	v_lshl_add_u64 v[2:3], s[0:1], 0, v[180:181]
	s_add_i32 m0, s70, 0x1e000
	v_and_b32_e32 v173, 15, v170
	global_load_lds_dwordx4 v[2:3], off
	s_waitcnt vmcnt(8)
	s_barrier
	v_lshlrev_b32_e32 v1, 1, v14
	v_lshlrev_b32_e32 v4, 6, v170
	s_movk_i32 s0, 0x3c0
	v_lshl_or_b32 v2, v173, 6, v1
	v_and_b32_e32 v3, 32, v172
	v_and_or_b32 v1, v4, s0, v1
	v_lshl_or_b32 v185, s6, 6, v173
	v_bitop3_b32 v210, s12, v1, v3 bitop3:0xf6
	s_lshl_b32 s6, s6, 9
	v_lshlrev_b32_e32 v1, 8, v173
	v_bitop3_b32 v2, v2, s5, v3 bitop3:0xde
	v_or_b32_e32 v184, s7, v14
	v_add_u32_e32 v3, s6, v1
	s_and_b32 s79, s3, 0xffffff00
	v_or_b32_e32 v3, v3, v184
	v_lshlrev_b32_e32 v3, 2, v3
	v_or_b32_e32 v1, v184, v1
	s_cmpk_gt_u32 s3, 0xff
	v_or_b32_e32 v211, s4, v15
	v_add_u32_e32 v212, 0xffffc800, v3
	v_add_u32_e32 v213, 0xffffd800, v3
	v_or_b32_e32 v3, 0xfffff000, v1
	s_cselect_b64 s[4:5], -1, 0
	s_add_i32 s3, s6, 0x400
	v_or_b32_e32 v1, 0xfffff004, v1
	v_add_lshl_u32 v217, v1, s6, 2
	v_add_lshl_u32 v218, v1, s3, 2
	v_lshlrev_b32_e32 v1, 8, v170
	v_add_lshl_u32 v215, v3, s6, 2
	v_add_lshl_u32 v216, v3, s3, 2
	v_and_b32_e32 v1, 0x38000, v1
	v_lshlrev_b32_e32 v3, 11, v12
	v_cmp_lt_u32_e64 s[0:1], 13, v173
	v_cmp_gt_u32_e32 vcc, 2, v173
	v_or3_b32 v1, v10, v1, v3
	s_and_b64 s[30:31], s[0:1], s[4:5]
	s_and_b64 s[34:35], s[14:15], vcc
	s_ashr_i32 s6, s33, 31
	s_ashr_i32 s92, s2, 31
	v_add_u32_e32 v186, v1, v11
	v_lshlrev_b32_e32 v1, 4, v13
	s_waitcnt vmcnt(6)
	s_add_u32 s36, s60, 0xb000
	v_and_b32_e32 v1, 0x78000, v1
	s_addc_u32 s37, s61, 0
	v_or3_b32 v1, v10, v1, v3
	s_add_i32 s93, 0, 0x10000
	s_add_i32 s90, 0, 0x14000
	v_add_u32_e32 v214, -14, v173
	v_mov_b32_e32 v187, v183
	v_add_u32_e32 v188, v1, v11
	v_mov_b32_e32 v189, v183
	v_mov_b64_e32 v[190:191], 0x580
	v_mov_b64_e32 v[192:193], 0x57f
	v_add_u32_e32 v219, s93, v210
	v_add_u32_e32 v220, s90, v210
	v_add_u32_e32 v221, 0, v2
	v_mov_b32_e32 v222, 0x358637bd
	s_add_i32 s91, 0, 0x20000
	s_add_i32 s97, 0, 0x20010
	s_add_i32 s96, 0, 0x20200
	s_add_i32 s87, 0, 0x20210
	s_movk_i32 s12, 0x1600
	v_lshlrev_b32_e32 v182, 1, v184
	s_barrier
	s_branch .LBB0_554

.LBB0_719:
	s_add_u32 s39, s88, 0x1c5000
	s_addc_u32 s40, s89, 0
	s_add_u32 s16, s88, 0x290000
	s_addc_u32 s17, s89, 0
	s_lshl_b32 s1, s1, 5
	s_mov_b64 s[18:19], 0x80
	s_and_b32 s22, s1, 0x60
	s_add_i32 m0, s34, 0x18000
	v_lshl_add_u64 v[8:9], v[8:9], 0, s[18:19]
	s_lshl_b32 s9, s0, 13
	s_lshl_b32 s1, s22, 7
	global_load_lds_dwordx4 v[8:9], off
	v_lshl_add_u64 v[6:7], v[6:7], 0, s[18:19]
	s_add_i32 m0, s34, 0x1a000
	s_add_i32 s41, s34, 0x8000
	s_add_i32 s42, s34, 0xa000
	global_load_lds_dwordx4 v[6:7], off
	v_lshl_add_u64 v[2:3], v[2:3], 0, s[18:19]
	s_mov_b32 m0, s41
	s_add_u32 s4, s26, 0xb0080
	global_load_lds_dwordx4 v[2:3], off
	v_lshl_add_u64 v[2:3], v[4:5], 0, s[18:19]
	s_mov_b32 m0, s42
	s_addc_u32 s5, s27, 0
	global_load_lds_dwordx4 v[2:3], off
	s_add_i32 m0, s34, 0x1c000
	v_lshl_add_u64 v[2:3], s[4:5], 0, v[156:157]
	global_load_lds_dwordx4 v[2:3], off
	v_lshl_add_u64 v[2:3], s[4:5], 0, v[160:161]
	s_add_i32 m0, s34, 0x1e000
	v_and_b32_e32 v1, 15, v170
	global_load_lds_dwordx4 v[2:3], off
	s_waitcnt vmcnt(8)
	s_barrier
	v_bfe_u32 v2, v170, 4, 2
	v_lshl_or_b32 v171, s0, 6, v1
	v_lshlrev_b32_e32 v3, 4, v2
	v_lshlrev_b32_e32 v5, 6, v170
	s_movk_i32 s0, 0x3c0
	v_lshl_or_b32 v1, v1, 6, v3
	v_and_b32_e32 v4, 32, v172
	v_and_or_b32 v3, v5, s0, v3
	v_bitop3_b32 v1, v1, s9, v4 bitop3:0xde
	v_bitop3_b32 v173, s1, v3, v4 bitop3:0xf6
	s_waitcnt vmcnt(6)
	s_cmpk_lt_u32 s8, 0x100
	v_cmp_eq_u32_e64 s[0:1], 0, v2
	v_lshl_or_b32 v175, v2, 3, s22
	v_add_u16_e32 v2, v10, v11
	s_cselect_b64 s[20:21], -1, 0
	v_lshrrev_b16_e32 v2, 1, v2
	s_add_i32 s43, 0, 0x10000
	s_add_i32 s44, 0, 0x14000
	v_add_u32_e32 v186, 0, v1
	v_mbcnt_lo_u32_b32 v1, -1, 0
	v_add_lshl_u32 v162, v12, v2, 1
	v_mov_b32_e32 v163, v157
	v_add_lshl_u32 v164, v13, v2, 1
	v_mov_b32_e32 v165, v157
	v_mov_b64_e32 v[166:167], 0x100
	v_mov_b64_e32 v[168:169], 0xff
	v_add_u32_e32 v184, s43, v173
	v_add_u32_e32 v185, s44, v173
	v_mbcnt_hi_u32_b32 v187, -1, v1
	s_barrier
	s_branch .LBB0_722

.LBB0_1194:
	s_add_u32 s55, s88, 0x1ce000
	s_addc_u32 s58, s89, 0
	s_add_u32 s59, s88, 0x2c2000
	s_addc_u32 s64, s89, 0
	s_add_u32 s16, s88, 0x2a0000
	s_addc_u32 s17, s89, 0
	s_lshl_b32 s1, s1, 5
	s_mov_b64 s[18:19], 0x80
	s_and_b32 s24, s1, 0x60
	s_add_i32 m0, s43, 0x18000
	v_lshl_add_u64 v[8:9], v[8:9], 0, s[18:19]
	s_lshl_b32 s9, s0, 13
	s_lshl_b32 s1, s24, 7
	global_load_lds_dwordx4 v[8:9], off
	v_lshl_add_u64 v[6:7], v[6:7], 0, s[18:19]
	s_add_i32 m0, s43, 0x1a000
	s_add_i32 s65, s43, 0x8000
	s_add_i32 s70, s43, 0xa000
	global_load_lds_dwordx4 v[6:7], off
	v_lshl_add_u64 v[2:3], v[2:3], 0, s[18:19]
	s_mov_b32 m0, s65
	s_add_u32 s4, s44, 0x10080
	global_load_lds_dwordx4 v[2:3], off
	v_lshl_add_u64 v[2:3], v[4:5], 0, s[18:19]
	s_mov_b32 m0, s70
	s_addc_u32 s5, s45, 0
	global_load_lds_dwordx4 v[2:3], off
	s_add_i32 m0, s43, 0x1c000
	v_lshl_add_u64 v[2:3], s[4:5], 0, v[148:149]
	global_load_lds_dwordx4 v[2:3], off
	v_lshl_add_u64 v[2:3], s[4:5], 0, v[152:153]
	s_add_i32 m0, s43, 0x1e000
	v_bfe_u32 v1, v170, 4, 2
	global_load_lds_dwordx4 v[2:3], off
	s_waitcnt vmcnt(8)
	s_barrier
	s_cmpk_lt_u32 s20, 0x100
	v_and_b32_e32 v0, 15, v170
	v_lshlrev_b32_e32 v2, 4, v1
	s_cselect_b64 s[20:21], -1, 0
	s_ashr_i32 s71, s33, 31
	s_ashr_i32 s4, s2, 31
	v_lshl_or_b32 v171, s0, 6, v0
	v_lshl_or_b32 v0, v0, 6, v2
	v_and_b32_e32 v3, 32, v172
	v_lshlrev_b32_e32 v4, 6, v170
	s_movk_i32 s0, 0x3c0
	s_cmp_lg_u64 s[56:57], 0
	v_bitop3_b32 v0, v0, s9, v3 bitop3:0xde
	v_and_or_b32 v2, v4, s0, v2
	s_waitcnt vmcnt(6)
	s_cselect_b64 s[22:23], -1, 0
	v_lshl_or_b32 v175, v1, 3, s24
	s_add_u32 s24, s33, s2
	v_bitop3_b32 v173, s1, v2, v3 bitop3:0xf6
	s_addc_u32 s25, s71, s4
	s_add_i32 s72, 0, 0x10000
	s_add_i32 s73, 0, 0x14000
	v_add_u32_e32 v192, 0, v0
	v_mbcnt_lo_u32_b32 v0, -1, 0
	v_cmp_eq_u32_e64 s[0:1], 0, v1
	s_mov_b64 s[26:27], 0x100
	v_add_u32_e32 v190, s72, v173
	v_add_u32_e32 v191, s73, v173
	s_mov_b64 s[28:29], 0x180
	v_mbcnt_hi_u32_b32 v193, -1, v0
	s_barrier
	s_branch .LBB0_1197

.LBB0_1311:
	s_add_u32 s26, s88, 0x2a00000
	s_addc_u32 s27, s89, 0
	s_add_u32 s28, s88, 0x2d00000
	s_addc_u32 s29, s89, 0
	s_lshl_b32 s0, s34, 5
	s_mov_b64 s[34:35], 0x80
	s_and_b32 s38, s0, 0x60
	s_add_i32 m0, s59, 0x18000
	v_lshl_add_u64 v[8:9], v[8:9], 0, s[34:35]
	s_lshl_b32 s5, s37, 13
	s_lshl_b32 s39, s38, 7
	global_load_lds_dwordx4 v[8:9], off
	v_lshl_add_u64 v[6:7], v[6:7], 0, s[34:35]
	s_add_i32 m0, s59, 0x1a000
	s_add_i32 s70, s59, 0x8000
	s_add_i32 s71, s59, 0xa000
	global_load_lds_dwordx4 v[6:7], off
	v_lshl_add_u64 v[2:3], v[2:3], 0, s[34:35]
	s_mov_b32 m0, s70
	s_add_u32 s0, s52, 0x40080
	global_load_lds_dwordx4 v[2:3], off
	v_lshl_add_u64 v[2:3], v[4:5], 0, s[34:35]
	s_mov_b32 m0, s71
	s_addc_u32 s1, s53, 0
	global_load_lds_dwordx4 v[2:3], off
	s_add_i32 m0, s59, 0x1c000
	v_lshl_add_u64 v[2:3], s[0:1], 0, v[178:179]
	global_load_lds_dwordx4 v[2:3], off
	v_lshl_add_u64 v[2:3], s[0:1], 0, v[182:183]
	s_add_i32 m0, s59, 0x1e000
	v_and_b32_e32 v1, 15, v170
	global_load_lds_dwordx4 v[2:3], off
	s_waitcnt vmcnt(8)
	s_barrier
	v_lshlrev_b32_e32 v2, 1, v14
	v_lshlrev_b32_e32 v5, 6, v170
	s_movk_i32 s0, 0x3c0
	v_lshl_or_b32 v3, v1, 6, v2
	v_and_b32_e32 v4, 32, v172
	v_and_or_b32 v2, v5, s0, v2
	v_bitop3_b32 v175, s39, v2, v4 bitop3:0xf6
	s_lshl_b32 s40, s37, 9
	v_lshlrev_b32_e32 v2, 8, v1
	v_bitop3_b32 v3, v3, s5, v4 bitop3:0xde
	v_or_b32_e32 v186, s38, v14
	s_and_b32 s72, s36, 0xffffff00
	v_add_u32_e32 v4, s40, v2
	v_or_b32_e32 v4, v4, v186
	s_cmpk_gt_u32 s36, 0xff
	v_or_b32_e32 v187, s4, v15
	v_cmp_lt_u32_e64 s[0:1], 13, v1
	v_lshlrev_b32_e32 v4, 2, v4
	v_or_b32_e32 v2, v186, v2
	s_cselect_b64 s[4:5], -1, 0
	v_lshl_or_b32 v173, s37, 6, v1
	v_add_u32_e32 v212, 0xffffc800, v4
	v_add_u32_e32 v213, 0xffffd800, v4
	v_or_b32_e32 v4, 0xfffff000, v2
	s_and_b64 s[36:37], s[0:1], s[4:5]
	s_add_i32 s4, s40, 0x400
	v_or_b32_e32 v2, 0xfffff004, v2
	v_add_lshl_u32 v217, v2, s40, 2
	v_add_lshl_u32 v218, v2, s4, 2
	v_lshlrev_b32_e32 v2, 8, v170
	v_add_lshl_u32 v215, v4, s40, 2
	v_add_lshl_u32 v216, v4, s4, 2
	v_and_b32_e32 v2, 0x38000, v2
	v_lshlrev_b32_e32 v4, 11, v12
	v_cmp_gt_u32_e32 vcc, 2, v1
	v_or3_b32 v2, v10, v2, v4
	s_and_b64 s[38:39], s[18:19], vcc
	s_ashr_i32 s73, s33, 31
	s_ashr_i32 s74, s2, 31
	v_add_u32_e32 v188, v2, v11
	v_lshlrev_b32_e32 v2, 4, v13
	s_waitcnt vmcnt(6)
	s_add_u32 s40, s60, 0x1b800
	v_and_b32_e32 v2, 0x78000, v2
	s_addc_u32 s41, s61, 0
	v_or3_b32 v2, v10, v2, v4
	s_add_i32 s75, 0, 0x10000
	s_add_i32 s76, 0, 0x14000
	v_add_u32_e32 v214, -14, v1
	v_mov_b32_e32 v189, v185
	v_add_u32_e32 v190, v2, v11
	v_mov_b32_e32 v191, v185
	v_mov_b64_e32 v[192:193], 0x580
	v_mov_b64_e32 v[194:195], 0x57f
	v_add_u32_e32 v219, s75, v175
	v_add_u32_e32 v220, s76, v175
	v_add_u32_e32 v221, 0, v3
	v_mov_b32_e32 v222, 0x358637bd
	s_add_i32 s77, 0, 0x20000
	s_add_i32 s78, 0, 0x20010
	s_add_i32 s79, 0, 0x20200
	s_add_i32 s80, 0, 0x20210
	s_movk_i32 s81, 0x1600
	v_lshlrev_b32_e32 v184, 1, v186
	s_barrier
	s_branch .LBB0_1314

.LBB0_1449:
	s_add_u32 s31, s88, 0x1d1000
	s_addc_u32 s34, s89, 0
	s_lshl_b32 s5, s5, 5
	s_mov_b64 s[8:9], 0x80
	s_and_b32 s5, s5, 0x60
	s_add_i32 m0, s26, 0x18000
	v_lshl_add_u64 v[6:7], v[6:7], 0, s[8:9]
	s_lshl_b32 s14, s0, 13
	s_lshl_b32 s15, s5, 7
	global_load_lds_dwordx4 v[6:7], off
	v_lshl_add_u64 v[4:5], v[4:5], 0, s[8:9]
	s_add_i32 m0, s26, 0x1a000
	s_add_i32 s35, s26, 0x8000
	s_add_i32 s36, s26, 0xa000
	global_load_lds_dwordx4 v[4:5], off
	v_lshl_add_u64 v[0:1], v[0:1], 0, s[8:9]
	s_mov_b32 m0, s35
	s_add_u32 s12, s18, 0xb0080
	global_load_lds_dwordx4 v[0:1], off
	v_lshl_add_u64 v[0:1], v[2:3], 0, s[8:9]
	s_mov_b32 m0, s36
	s_addc_u32 s13, s19, 0
	global_load_lds_dwordx4 v[0:1], off
	s_add_i32 m0, s26, 0x1c000
	v_lshl_add_u64 v[0:1], s[12:13], 0, v[146:147]
	global_load_lds_dwordx4 v[0:1], off
	v_lshl_add_u64 v[0:1], s[12:13], 0, v[150:151]
	s_add_i32 m0, s26, 0x1e000
	v_lshlrev_b32_e32 v3, 6, v170
	global_load_lds_dwordx4 v[0:1], off
	s_waitcnt vmcnt(8)
	s_barrier
	v_and_b32_e32 v0, 15, v170
	v_lshl_or_b32 v166, s0, 6, v0
	v_lshlrev_b32_e32 v1, 1, v10
	s_movk_i32 s0, 0x3c0
	v_lshl_or_b32 v0, v0, 6, v1
	v_and_b32_e32 v2, 32, v172
	v_and_or_b32 v1, v3, s0, v1
	v_bitop3_b32 v167, s15, v1, v2 bitop3:0xf6
	s_waitcnt vmcnt(6)
	s_cmpk_lt_u32 s4, 0x100
	v_add_u16_e32 v1, v8, v9
	v_bitop3_b32 v0, v0, s14, v2 bitop3:0xde
	s_cselect_b64 s[12:13], -1, 0
	v_lshrrev_b16_e32 v1, 1, v1
	s_add_i32 s37, 0, 0x10000
	s_add_i32 s38, 0, 0x14000
	s_sext_i32_i8 s42, s1
	v_or_b32_e32 v168, s5, v10
	v_add_lshl_u32 v152, v11, v1, 1
	v_mov_b32_e32 v153, v147
	v_add_lshl_u32 v154, v12, v1, 1
	v_mov_b32_e32 v155, v147
	v_mov_b64_e32 v[156:157], 0x100
	v_mov_b64_e32 v[158:159], 0xff
	v_add_u32_e32 v169, s37, v167
	v_add_u32_e32 v170, s38, v167
	v_add_u32_e32 v171, 0, v0
	s_barrier
	s_branch .LBB0_1452
